# GEMM phase prologues: second group of initial stage DMA loads issued before the first wait+barrier (one exposed load latency less per GEMM phase)
# speedup vs baseline: 1.0116x; 1.0046x over previous
; #define PG8_STAGE(bufoff, gbase, voff) do { _Pragma("unroll") for (int _i = 0; _i < 2; ++_i) \
;         __builtin_amdgcn_global_load_lds((const unsigned*)((const char*)(gbase) + (voff)[_i]), (LAS unsigned*)(lds + (bufoff) + ldsw + _i * 8192), 16, 0, 0); } while (0)
; #define PG8_WAIT_V(n) asm volatile("s_waitcnt vmcnt(" #n ")" ::: "memory")
; #define PG8_BAR __builtin_amdgcn_s_barrier()
; template <bool GATHER, bool FP8, class Epi, class Sched>
; __device__ __forceinline__ void gemm_phase(LAS unsigned char* lds, const int tid, const int K, const Sched& S, const Epi& E) {
;     ...
;     const unsigned ldsw = (unsigned)wid * 1024u;
;     const int aoff = lds_byte(wr * 64 + fr, fq * 8), boff = lds_byte(wc * 32 + fr, fq * 8);
;     ...
;     PG8_STAGE(PG8_SB(0, 0), cB, voffB); PG8_STAGE(PG8_SB(0, 1), cB + hstepB, voffB); PG8_STAGE(PG8_SA(0, 0), cA, oC[0]); PG8_STAGE(PG8_SA(0, 1), cA + hsA, oC[1]);
;     if (wr == 1) PG8_BAR;
;     PG8_WAIT_V(2); PG8_BAR;
;     PG8_STAGE(PG8_SB(1, 0), cB + kstepB, voffB); PG8_STAGE(PG8_SA(1, 0), cA + kstep, oC[0]); PG8_STAGE(PG8_SB(1, 1), cB + hstepB + kstepB, voffB);
;     PG8_WAIT_V(6); PG8_BAR;
.LBB0_31:
	s_lshl_b32 s1, s26, 5
	s_and_b32 s67, s1, 0x60
	s_lshl_b32 s66, s27, 6
	s_lshl_b32 s0, s27, 13
	s_lshl_b32 s1, s67, 7
	s_add_u32 s16, s22, 0x8000
	v_mov_b32_e32 v175, v33
	s_addc_u32 s17, s23, 0
	s_add_i32 s70, s41, 0x18000
	v_mov_b32_e32 v177, v33
	v_lshl_add_u64 v[8:9], s[16:17], 0, v[174:175]
	s_mov_b32 m0, s70
	s_add_i32 s71, s41, 0x1a000
	global_load_lds_dwordx4 v[8:9], off
	v_lshl_add_u64 v[8:9], s[16:17], 0, v[176:177]
	s_mov_b32 m0, s71
	s_add_i32 s72, s41, 0x8000
	s_add_i32 s73, s41, 0xa000
	global_load_lds_dwordx4 v[8:9], off
	v_lshl_add_u64 v[0:1], v[0:1], 0, s[24:25]
	s_mov_b32 m0, s72
	s_add_u32 s16, s22, 0xc000
	global_load_lds_dwordx4 v[0:1], off
	v_lshl_add_u64 v[0:1], v[2:3], 0, s[24:25]
	s_mov_b32 m0, s73
	s_addc_u32 s17, s23, 0
	s_add_i32 s93, s41, 0x1c000
	global_load_lds_dwordx4 v[0:1], off
	v_lshl_add_u64 v[0:1], s[16:17], 0, v[174:175]
	s_mov_b32 m0, s93
	s_add_i32 s94, s41, 0x1e000
	global_load_lds_dwordx4 v[0:1], off
	v_lshl_add_u64 v[0:1], s[16:17], 0, v[176:177]
	s_mov_b32 m0, s94
	v_lshlrev_b32_e32 v2, 2, v168
	global_load_lds_dwordx4 v[0:1], off
	s_waitcnt vmcnt(8)
	s_barrier
	v_lshlrev_b32_e32 v1, 6, v168
	v_and_b32_e32 v0, 48, v168
	v_and_b32_e32 v1, 0x3c0, v1
	v_and_b32_e32 v2, 32, v2
	v_bitop3_b32 v0, v1, v2, v0 bitop3:0x36
	s_add_i32 s1, s1, 0
	v_add_u32_e32 v1, s1, v0
	v_add_u32_e32 v212, 0x10000, v1
	v_add_u32_e32 v213, 0x10400, v1
	v_add_u32_e32 v214, 0x10800, v1
	v_add_u32_e32 v215, 0x10c00, v1
	v_add_u32_e32 v216, 0x14000, v1
	v_add_u32_e32 v217, 0x14400, v1
	v_add_u32_e32 v218, 0x14800, v1
	v_add_u32_e32 v219, 0x14c00, v1
	v_add_u32_e32 v220, 0x18000, v1
	v_add_u32_e32 v221, 0x18400, v1
	v_add_u32_e32 v222, 0x18800, v1
	v_add_u32_e32 v223, 0x18c00, v1
	v_add_u32_e32 v224, 0x1c000, v1
	v_add_u32_e32 v225, 0x1c400, v1
	v_add_u32_e32 v226, 0x1c800, v1
	v_add_u32_e32 v227, 0x1cc00, v1
	v_lshlrev_b32_e32 v1, 13, v4
	v_and_b32_e32 v1, 0xffffc000, v1
	v_lshl_add_u32 v1, v5, 10, v1
	v_and_b32_e32 v2, 1, v4
	s_waitcnt vmcnt(6)
	v_lshl_or_b32 v1, v2, 6, v1
	v_add_u32_e32 v0, 0, v0
	s_cmpk_lt_u32 s12, 0x100
	v_readlane_b32 s1, v249, 49
	v_lshl_add_u32 v178, v6, 1, v1
	s_cselect_b64 s[36:37], -1, 0
	s_ashr_i32 s95, s1, 5
	v_mov_b32_e32 v179, v33
	v_add_u32_e32 v180, 0x10000, v178
	v_mov_b32_e32 v181, v33
	s_mov_b32 s16, 0
	v_add_u32_e32 v228, s0, v0
	s_barrier
	s_branch .LBB0_35

; #define PG8_STAGE(bufoff, gbase, voff) do { _Pragma("unroll") for (int _i = 0; _i < 2; ++_i) \
;         __builtin_amdgcn_global_load_lds((const unsigned*)((const char*)(gbase) + (voff)[_i]), (LAS unsigned*)(lds + (bufoff) + ldsw + _i * 8192), 16, 0, 0); } while (0)
; #define PG8_WAIT_V(n) asm volatile("s_waitcnt vmcnt(" #n ")" ::: "memory")
; #define PG8_BAR __builtin_amdgcn_s_barrier()
; template <bool GATHER, bool FP8, class Epi, class Sched>
; __device__ __forceinline__ void gemm_phase(LAS unsigned char* lds, const int tid, const int K, const Sched& S, const Epi& E) {
;     ...
;     const unsigned ldsw = (unsigned)wid * 1024u;
;     const int aoff = lds_byte(wr * 64 + fr, fq * 8), boff = lds_byte(wc * 32 + fr, fq * 8);
;     ...
;     PG8_STAGE(PG8_SB(0, 0), cB, voffB); PG8_STAGE(PG8_SB(0, 1), cB + hstepB, voffB); PG8_STAGE(PG8_SA(0, 0), cA, oC[0]); PG8_STAGE(PG8_SA(0, 1), cA + hsA, oC[1]);
;     if (wr == 1) PG8_BAR;
;     PG8_WAIT_V(2); PG8_BAR;
;     PG8_STAGE(PG8_SB(1, 0), cB + kstepB, voffB); PG8_STAGE(PG8_SA(1, 0), cA + kstep, oC[0]); PG8_STAGE(PG8_SB(1, 1), cB + hstepB + kstepB, voffB);
;     PG8_WAIT_V(6); PG8_BAR;
.LBB0_84:
	s_and_b32 s21, s27, 3
	s_lshl_b32 s61, s26, 6
	s_lshl_b32 s26, s26, 13
	s_lshl_b32 s27, s21, 12
	s_add_u32 s16, s22, 0x8000
	v_mov_b32_e32 v173, v33
	s_addc_u32 s17, s23, 0
	s_add_i32 s62, s47, 0x18000
	v_mov_b32_e32 v175, v33
	v_lshl_add_u64 v[0:1], s[16:17], 0, v[172:173]
	s_mov_b32 m0, s62
	global_load_lds_dwordx4 v[0:1], off
	v_lshl_add_u64 v[0:1], s[16:17], 0, v[174:175]
	s_add_i32 s63, s47, 0x1a000
	v_readlane_b32 s16, v251, 39
	s_mov_b32 m0, s63
	v_readlane_b32 s17, v251, 40
	s_add_i32 s64, s47, 0x8000
	v_mov_b32_e32 v177, v33
	global_load_lds_dwordx4 v[0:1], off
	v_lshl_add_u64 v[0:1], s[16:17], 0, v[32:33]
	s_mov_b32 m0, s64
	s_add_i32 s65, s47, 0xa000
	global_load_lds_dwordx4 v[0:1], off
	v_lshl_add_u64 v[0:1], s[16:17], 0, v[176:177]
	s_add_u32 s16, s22, 0xc000
	s_mov_b32 m0, s65
	s_addc_u32 s17, s23, 0
	s_add_i32 s66, s47, 0x1c000
	global_load_lds_dwordx4 v[0:1], off
	v_lshl_add_u64 v[0:1], s[16:17], 0, v[172:173]
	s_mov_b32 m0, s66
	s_add_i32 s67, s47, 0x1e000
	global_load_lds_dwordx4 v[0:1], off
	v_lshl_add_u64 v[0:1], s[16:17], 0, v[174:175]
	s_mov_b32 m0, s67
	s_cmp_lt_u32 s12, 64
	global_load_lds_dwordx4 v[0:1], off
	s_waitcnt vmcnt(8)
	s_barrier
	s_cselect_b64 s[36:37], -1, 0
	s_add_i32 s16, s27, 0
	v_lshlrev_b32_e32 v1, 6, v168
	v_lshlrev_b32_e32 v2, 2, v168
	s_cmpk_lt_u32 s12, 0x100
	v_readlane_b32 s12, v249, 49
	v_and_b32_e32 v0, 48, v168
	v_and_b32_e32 v1, 0x3c0, v1
	v_and_b32_e32 v2, 32, v2
	s_cselect_b64 s[38:39], -1, 0
	s_ashr_i32 s12, s12, 6
	v_bitop3_b32 v0, v1, v2, v0 bitop3:0x36
	s_waitcnt vmcnt(6)
	v_writelane_b32 v249, s12, 52
	s_lshl_b32 s12, s21, 6
	v_add_u32_e32 v1, s16, v0
	v_add_u32_e32 v0, 0, v0
	s_add_i32 s72, s12, 0
	s_lshl_b32 s70, s21, 4
	v_add_u32_e32 v191, 0x10000, v1
	v_add_u32_e32 v192, 0x10400, v1
	v_add_u32_e32 v194, 0x10800, v1
	v_add_u32_e32 v195, 0x10c00, v1
	v_add_u32_e32 v196, 0x14000, v1
	v_add_u32_e32 v197, 0x14400, v1
	v_add_u32_e32 v212, 0x14800, v1
	v_add_u32_e32 v213, 0x14c00, v1
	v_add_u32_e32 v214, 0x18000, v1
	v_add_u32_e32 v215, 0x18400, v1
	v_add_u32_e32 v216, 0x18800, v1
	v_add_u32_e32 v217, 0x18c00, v1
	v_add_u32_e32 v218, 0x1c000, v1
	v_add_u32_e32 v219, 0x1c400, v1
	v_add_u32_e32 v220, 0x1c800, v1
	v_add_u32_e32 v221, 0x1cc00, v1
	s_add_i32 s72, s72, 0x24040
	s_mov_b32 s95, 0
	v_add_u32_e32 v222, s26, v0
	s_barrier
	s_branch .LBB0_87

; #define PG8_STAGE(bufoff, gbase, voff) do { _Pragma("unroll") for (int _i = 0; _i < 2; ++_i) \
;         __builtin_amdgcn_global_load_lds((const unsigned*)((const char*)(gbase) + (voff)[_i]), (LAS unsigned*)(lds + (bufoff) + ldsw + _i * 8192), 16, 0, 0); } while (0)
; #define PG8_WAIT_V(n) asm volatile("s_waitcnt vmcnt(" #n ")" ::: "memory")
; #define PG8_BAR __builtin_amdgcn_s_barrier()
; template <bool GATHER, bool FP8, class Epi, class Sched>
; __device__ __forceinline__ void gemm_phase(LAS unsigned char* lds, const int tid, const int K, const Sched& S, const Epi& E) {
;     ...
;     int R0, C0; stage_rc(tid * 16, R0, C0); const int Rb0 = Epi::PERM ? ((R0 & ~31) + perm32(R0 & 31)) : R0;
;     unsigned voffA[2], voffB[2];
;     voffA[0] = (unsigned)(R0 * K + C0) * 2u; voffA[1] = voffA[0] + (unsigned)(64 * K * 2);
;     voffB[0] = (unsigned)(Rb0 * 128 + C0 * 2); voffB[1] = voffB[0] + 64u * 128u;
;     const size_t kstepB = 32768, hstepB = 16384;
;     const size_t kstep = (size_t)(BK * 2);
;     const size_t hstep = (size_t)HALF * K * 2;
;     const size_t hsA = GATHER ? (size_t)0 : hstep;
;     unsigned oC[2][2], o2[2][2];
;     ...
;     const unsigned ldsw = (unsigned)wid * 1024u;
;     const int aoff = lds_byte(wr * 64 + fr, fq * 8), boff = lds_byte(wc * 32 + fr, fq * 8);
;     ...
;     PG8_STAGE(PG8_SB(0, 0), cB, voffB); PG8_STAGE(PG8_SB(0, 1), cB + hstepB, voffB); PG8_STAGE(PG8_SA(0, 0), cA, oC[0]); PG8_STAGE(PG8_SA(0, 1), cA + hsA, oC[1]);
;     if (wr == 1) PG8_BAR;
;     PG8_WAIT_V(2); PG8_BAR;
;     PG8_STAGE(PG8_SB(1, 0), cB + kstepB, voffB); PG8_STAGE(PG8_SA(1, 0), cA + kstep, oC[0]); PG8_STAGE(PG8_SB(1, 1), cB + hstepB + kstepB, voffB);
;     PG8_WAIT_V(6); PG8_BAR;
.LBB0_152:
	v_and_b32_e32 v3, 48, v168
	v_lshlrev_b32_e32 v8, 6, v168
	s_movk_i32 s20, 0x3c0
	s_lshl_b32 s16, s16, 5
	v_and_or_b32 v3, v8, s20, v3
	v_lshlrev_b32_e32 v8, 2, v168
	s_and_b32 s55, s16, 0x60
	s_lshl_b32 s54, s17, 6
	s_lshl_b32 s17, s17, 13
	v_and_b32_e32 v8, 32, v8
	s_lshl_b32 s16, s55, 7
	s_waitcnt vmcnt(0)
	v_bitop3_b32 v10, v3, s17, v8 bitop3:0xde
	v_bitop3_b32 v169, s16, v3, v8 bitop3:0xf6
	v_readlane_b32 s16, v249, 42
	v_readlane_b32 s26, v253, 34
	v_readlane_b32 s17, v249, 43
	v_mov_b32_e32 v149, v33
	v_mov_b32_e32 v151, v33
	v_readlane_b32 s27, v253, 35
	s_add_i32 m0, s50, 0x18000
	v_lshl_add_u64 v[8:9], s[16:17], 0, v[32:33]
	v_lshl_add_u64 v[4:5], s[26:27], 0, v[150:151]
	v_mov_b32_e32 v153, v33
	global_load_lds_dwordx4 v[8:9], off
	v_lshl_add_u64 v[8:9], s[16:17], 0, v[148:149]
	s_add_i32 m0, s50, 0x1a000
	s_add_i32 s56, s50, 0x8000
	v_lshl_add_u64 v[6:7], s[26:27], 0, v[152:153]
	global_load_lds_dwordx4 v[8:9], off
	v_lshl_add_u64 v[4:5], v[4:5], 0, s[24:25]
	s_mov_b32 m0, s56
	s_add_i32 s57, s50, 0xa000
	v_readlane_b32 s16, v249, 46
	global_load_lds_dwordx4 v[4:5], off
	v_lshl_add_u64 v[4:5], v[6:7], 0, s[24:25]
	s_mov_b32 m0, s57
	v_readlane_b32 s17, v249, 47
	global_load_lds_dwordx4 v[4:5], off
	s_add_i32 m0, s50, 0x1c000
	v_lshl_add_u64 v[4:5], s[16:17], 0, v[32:33]
	global_load_lds_dwordx4 v[4:5], off
	v_lshl_add_u64 v[4:5], s[16:17], 0, v[148:149]
	s_add_i32 m0, s50, 0x1e000
	v_lshlrev_b32_e32 v3, 14, v1
	global_load_lds_dwordx4 v[4:5], off
	s_waitcnt vmcnt(8)
	s_barrier
	v_and_b32_e32 v3, 0xffff8000, v3
	v_lshl_add_u32 v0, v0, 11, v3
	v_and_b32_e32 v1, 1, v1
	s_waitcnt vmcnt(6)
	v_lshl_or_b32 v0, v1, 6, v0
	v_readlane_b32 s20, v253, 32
	s_cmpk_lt_u32 s12, 0x100
	v_readlane_b32 s12, v249, 49
	v_lshl_add_u32 v154, v2, 1, v0
	v_readlane_b32 s21, v253, 33
	v_readlane_b32 s22, v249, 44
	s_cselect_b64 s[16:17], -1, 0
	s_ashr_i32 s58, s12, 31
	v_mov_b32_e32 v155, v33
	v_add_u32_e32 v156, 0x20000, v154
	v_mov_b32_e32 v157, v33
	s_mov_b32 s59, 0
	v_add_u32_e32 v174, 0, v10
	v_readlane_b32 s12, v253, 29
	s_mov_b32 s60, s20
	v_readlane_b32 s23, v249, 45
	s_mov_b64 s[20:21], s[26:27]
	s_barrier
	s_branch .LBB0_155

; #define PG8_STAGE(bufoff, gbase, voff) do { _Pragma("unroll") for (int _i = 0; _i < 2; ++_i) \
;         __builtin_amdgcn_global_load_lds((const unsigned*)((const char*)(gbase) + (voff)[_i]), (LAS unsigned*)(lds + (bufoff) + ldsw + _i * 8192), 16, 0, 0); } while (0)
; #define PG8_WAIT_V(n) asm volatile("s_waitcnt vmcnt(" #n ")" ::: "memory")
; #define PG8_BAR __builtin_amdgcn_s_barrier()
; template <bool GATHER, bool FP8, class Epi, class Sched>
; __device__ __forceinline__ void gemm_phase(LAS unsigned char* lds, const int tid, const int K, const Sched& S, const Epi& E) {
;     ...
;     int R0, C0; stage_rc(tid * 16, R0, C0); const int Rb0 = Epi::PERM ? ((R0 & ~31) + perm32(R0 & 31)) : R0;
;     unsigned voffA[2], voffB[2];
;     voffA[0] = (unsigned)(R0 * K + C0) * 2u; voffA[1] = voffA[0] + (unsigned)(64 * K * 2);
;     voffB[0] = (unsigned)(Rb0 * 128 + C0 * 2); voffB[1] = voffB[0] + 64u * 128u;
;     const size_t kstepB = 32768, hstepB = 16384;
;     const size_t kstep = (size_t)(BK * 2);
;     const size_t hstep = (size_t)HALF * K * 2;
;     const size_t hsA = GATHER ? (size_t)0 : hstep;
;     unsigned oC[2][2], o2[2][2];
;     ...
;     const unsigned ldsw = (unsigned)wid * 1024u;
;     const int aoff = lds_byte(wr * 64 + fr, fq * 8), boff = lds_byte(wc * 32 + fr, fq * 8);
;     ...
;     PG8_STAGE(PG8_SB(0, 0), cB, voffB); PG8_STAGE(PG8_SB(0, 1), cB + hstepB, voffB); PG8_STAGE(PG8_SA(0, 0), cA, oC[0]); PG8_STAGE(PG8_SA(0, 1), cA + hsA, oC[1]);
;     if (wr == 1) PG8_BAR;
;     PG8_WAIT_V(2); PG8_BAR;
;     PG8_STAGE(PG8_SB(1, 0), cB + kstepB, voffB); PG8_STAGE(PG8_SA(1, 0), cA + kstep, oC[0]); PG8_STAGE(PG8_SB(1, 1), cB + hstepB + kstepB, voffB);
;     PG8_WAIT_V(6); PG8_BAR;
.LBB0_377:
	v_readlane_b32 s22, v249, 19
	v_readlane_b32 s26, v252, 12
	v_readlane_b32 s23, v249, 20
	v_mov_b32_e32 v149, v33
	v_mov_b32_e32 v151, v33
	v_readlane_b32 s27, v252, 13
	s_add_i32 m0, s15, 0x18000
	v_lshl_add_u64 v[8:9], s[22:23], 0, v[32:33]
	v_lshl_add_u64 v[4:5], s[26:27], 0, v[150:151]
	v_mov_b32_e32 v153, v33
	global_load_lds_dwordx4 v[8:9], off
	v_lshl_add_u64 v[8:9], s[22:23], 0, v[148:149]
	s_add_i32 m0, s15, 0x1a000
	s_add_i32 s51, s15, 0x8000
	v_lshl_add_u64 v[6:7], s[26:27], 0, v[152:153]
	global_load_lds_dwordx4 v[8:9], off
	v_lshl_add_u64 v[4:5], v[4:5], 0, s[24:25]
	s_mov_b32 m0, s51
	s_add_i32 s52, s15, 0xa000
	v_readlane_b32 s22, v249, 23
	global_load_lds_dwordx4 v[4:5], off
	v_lshl_add_u64 v[4:5], v[6:7], 0, s[24:25]
	s_mov_b32 m0, s52
	v_readlane_b32 s23, v249, 24
	global_load_lds_dwordx4 v[4:5], off
	s_add_i32 m0, s15, 0x1c000
	v_lshl_add_u64 v[4:5], s[22:23], 0, v[32:33]
	global_load_lds_dwordx4 v[4:5], off
	v_lshl_add_u64 v[4:5], s[22:23], 0, v[148:149]
	s_add_i32 m0, s15, 0x1e000
	v_and_b32_e32 v3, 48, v168
	global_load_lds_dwordx4 v[4:5], off
	s_waitcnt vmcnt(8)
	s_barrier
	v_lshlrev_b32_e32 v4, 6, v168
	s_movk_i32 s21, 0x3c0
	s_lshl_b32 s17, s17, 5
	v_and_or_b32 v3, v4, s21, v3
	v_lshlrev_b32_e32 v4, 2, v168
	s_and_b32 s54, s17, 0x60
	s_lshl_b32 s53, s20, 6
	s_lshl_b32 s20, s20, 13
	v_and_b32_e32 v4, 32, v4
	s_lshl_b32 s17, s54, 7
	v_bitop3_b32 v5, v3, s20, v4 bitop3:0xde
	v_bitop3_b32 v162, s17, v3, v4 bitop3:0xf6
	v_lshlrev_b32_e32 v3, 14, v1
	v_and_b32_e32 v3, 0xffff8000, v3
	s_cmpk_lt_u32 s16, 0x100
	v_readlane_b32 s20, v249, 49
	v_lshl_add_u32 v0, v0, 11, v3
	v_and_b32_e32 v1, 1, v1
	s_waitcnt vmcnt(6)
	s_cselect_b64 s[16:17], -1, 0
	s_ashr_i32 s55, s20, 31
	v_lshl_or_b32 v0, v1, 6, v0
	v_readlane_b32 s20, v252, 8
	v_lshl_add_u32 v154, v2, 1, v0
	v_readlane_b32 s21, v252, 9
	v_readlane_b32 s22, v249, 21
	v_mov_b32_e32 v155, v33
	v_add_u32_e32 v156, 0x20000, v154
	v_mov_b32_e32 v157, v33
	s_mov_b32 s56, 0
	v_add_u32_e32 v163, 0, v5
	v_readlane_b32 s57, v252, 5
	s_mov_b32 s58, s20
	v_readlane_b32 s23, v249, 22
	s_mov_b64 s[20:21], s[26:27]
	s_barrier
	s_branch .LBB0_380
